# v002 plus: dilated far tiles update O in place (no copy out and back), diff QK(0) K-fragment reads batched under counted lgkmcnt
# speedup vs baseline: 1.0107x; 1.0083x over previous
.LBB0_292:
	v_sub_f32_e32 v66, v66, v223
	v_exp_f32_e32 v70, v66
	v_sub_f32_e32 v66, v67, v223
	v_exp_f32_e32 v72, v66
	v_sub_f32_e32 v66, v68, v223
	v_exp_f32_e32 v71, v66
	v_sub_f32_e32 v66, v69, v223
	v_exp_f32_e32 v73, v66
	v_mov_b32_e32 v237, v223
	v_pk_mul_f32 v[66:67], v[178:179], v[70:71] op_sel_hi:[1,0]
	v_pk_mul_f32 v[68:69], v[180:181], v[70:71] op_sel_hi:[1,0]
	v_pk_mul_f32 v[74:75], v[178:179], v[72:73] op_sel_hi:[1,0]
	v_pk_mul_f32 v[76:77], v[180:181], v[72:73] op_sel_hi:[1,0]
	v_cvt_pk_bf16_f32 v66, v66, v67
	v_cvt_pk_bf16_f32 v67, v68, v69
	v_cvt_pk_bf16_f32 v68, v74, v75
	v_cvt_pk_bf16_f32 v69, v76, v77
	v_mov_b32_e32 v74, v71
	v_pk_mul_f32 v[76:77], v[178:179], v[74:75] op_sel_hi:[1,0]
	v_mfma_f32_32x32x16_bf16 v[50:65], v[94:97], v[66:69], v[50:65]
	v_pk_mul_f32 v[74:75], v[180:181], v[74:75] op_sel_hi:[1,0]
	v_pk_add_f32 v[70:71], v[70:71], v[72:73]
	s_nop 0
	v_add_f32_e32 v70, v70, v71
	v_add_f32_e32 v238, v221, v70
	v_mfma_f32_32x32x16_bf16 v[34:49], v[90:93], v[66:69], v[34:49]
	v_mov_b32_e32 v66, v73
	v_mul_f32_e64 v68, v178, v66
	v_mul_f32_e64 v69, v179, v66
	v_mul_f32_e64 v78, v180, v66
	v_mul_f32_e64 v79, v181, v66
	v_cvt_pk_bf16_f32 v66, v76, v77
	v_cvt_pk_bf16_f32 v67, v74, v75
	v_cvt_pk_bf16_f32 v68, v68, v69
	v_cvt_pk_bf16_f32 v69, v78, v79
	s_nop 1
	v_mfma_f32_32x32x16_bf16 v[50:65], v[86:89], v[66:69], v[50:65]
	v_mfma_f32_32x32x16_bf16 v[34:49], v[82:85], v[66:69], v[34:49]
	v_mov_b32_e32 v221, v238
	s_branch .Ldil_join0

.Ldil_join0:
	s_sub_i32 s13, s12, s63
	s_cmp_gt_u32 s13, 16
	s_cbranch_scc1 .LBB0_279

.LBB0_306:
	v_sub_f32_e32 v66, v66, v222
	v_exp_f32_e32 v70, v66
	v_sub_f32_e32 v66, v67, v222
	v_exp_f32_e32 v72, v66
	v_sub_f32_e32 v66, v68, v222
	v_exp_f32_e32 v71, v66
	v_sub_f32_e32 v66, v69, v222
	v_exp_f32_e32 v73, v66
	v_mov_b32_e32 v239, v222
	v_pk_mul_f32 v[66:67], v[178:179], v[70:71] op_sel_hi:[1,0]
	v_pk_mul_f32 v[68:69], v[180:181], v[70:71] op_sel_hi:[1,0]
	v_pk_mul_f32 v[74:75], v[178:179], v[72:73] op_sel_hi:[1,0]
	v_pk_mul_f32 v[76:77], v[180:181], v[72:73] op_sel_hi:[1,0]
	v_cvt_pk_bf16_f32 v66, v66, v67
	v_cvt_pk_bf16_f32 v67, v68, v69
	v_cvt_pk_bf16_f32 v68, v74, v75
	v_cvt_pk_bf16_f32 v69, v76, v77
	v_mov_b32_e32 v74, v71
	v_pk_mul_f32 v[76:77], v[178:179], v[74:75] op_sel_hi:[1,0]
	v_mfma_f32_32x32x16_bf16 v[18:33], v[94:97], v[66:69], v[18:33]
	v_pk_mul_f32 v[74:75], v[180:181], v[74:75] op_sel_hi:[1,0]
	v_pk_add_f32 v[70:71], v[70:71], v[72:73]
	s_nop 0
	v_add_f32_e32 v70, v70, v71
	v_add_f32_e32 v240, v220, v70
	v_mfma_f32_32x32x16_bf16 v[2:17], v[90:93], v[66:69], v[2:17]
	v_mov_b32_e32 v66, v73
	v_mul_f32_e64 v68, v178, v66
	v_mul_f32_e64 v69, v179, v66
	v_mul_f32_e64 v78, v180, v66
	v_mul_f32_e64 v79, v181, v66
	v_cvt_pk_bf16_f32 v66, v76, v77
	v_cvt_pk_bf16_f32 v67, v74, v75
	v_cvt_pk_bf16_f32 v68, v68, v69
	v_cvt_pk_bf16_f32 v69, v78, v79
	s_nop 1
	v_mfma_f32_32x32x16_bf16 v[18:33], v[86:89], v[66:69], v[18:33]
	v_mfma_f32_32x32x16_bf16 v[2:17], v[82:85], v[66:69], v[2:17]
	v_mov_b32_e32 v220, v240
	s_branch .Ldil_join1
.LBB0_307:
	s_nop 7
	v_mov_b64_e32 v[2:3], v[82:83]
	v_mov_b64_e32 v[18:19], v[66:67]
	v_mov_b32_e32 v220, v240
	v_mov_b32_e32 v222, v239
	v_mov_b64_e32 v[4:5], v[84:85]
	v_mov_b64_e32 v[6:7], v[86:87]
	v_mov_b64_e32 v[8:9], v[88:89]
	v_mov_b64_e32 v[10:11], v[90:91]
	v_mov_b64_e32 v[12:13], v[92:93]
	v_mov_b64_e32 v[14:15], v[94:95]
	v_mov_b64_e32 v[16:17], v[96:97]
	v_mov_b64_e32 v[20:21], v[68:69]
	v_mov_b64_e32 v[22:23], v[70:71]
	v_mov_b64_e32 v[24:25], v[72:73]
	v_mov_b64_e32 v[26:27], v[74:75]
	v_mov_b64_e32 v[28:29], v[76:77]
	v_mov_b64_e32 v[30:31], v[78:79]
	v_mov_b64_e32 v[32:33], v[80:81]
.Ldil_join1:
	s_xor_b64 s[12:13], s[50:51], -1
	s_and_b64 vcc, exec, s[48:49]
	s_cbranch_vccz .LBB0_276
.LBB0_308:
	s_mov_b64 s[4:5], -1
	s_and_b64 vcc, exec, s[12:13]
	v_add_u32_e32 v66, s67, v215
	s_cbranch_vccz .LBB0_310
	s_waitcnt vmcnt(0) lgkmcnt(0)
	ds_write_b128 v66, v[146:149]
	s_mov_b64 s[4:5], 0

.LBB0_377:
	s_mul_i32 s14, s48, 0x8800
	v_add_u32_e32 v6, s14, v193
	s_setprio 1
	ds_read_b128 v[2:5], v6
	ds_read_b128 v[112:115], v6 offset:32
	ds_read_b128 v[116:119], v6 offset:64
	ds_read_b128 v[120:123], v6 offset:96
	ds_read_b128 v[124:127], v6 offset:8704
	ds_read_b128 v[128:131], v6 offset:8736
	ds_read_b128 v[132:135], v6 offset:8768
	ds_read_b128 v[136:139], v6 offset:8800
	s_waitcnt lgkmcnt(7)
	v_mfma_f32_32x32x16_bf16 v[96:111], v[2:5], v[156:159], 0
	s_waitcnt lgkmcnt(6)
	v_mfma_f32_32x32x16_bf16 v[96:111], v[112:115], v[152:155], v[96:111]
	s_waitcnt lgkmcnt(5)
	v_mfma_f32_32x32x16_bf16 v[96:111], v[116:119], v[148:151], v[96:111]
	s_waitcnt lgkmcnt(4)
	v_mfma_f32_32x32x16_bf16 v[96:111], v[120:123], v[144:147], v[96:111]
	s_waitcnt lgkmcnt(3)
	v_mfma_f32_32x32x16_bf16 v[80:95], v[124:127], v[156:159], 0
	s_waitcnt lgkmcnt(2)
	v_mfma_f32_32x32x16_bf16 v[80:95], v[128:131], v[152:155], v[80:95]
	s_waitcnt lgkmcnt(1)
	v_mfma_f32_32x32x16_bf16 v[80:95], v[132:135], v[148:151], v[80:95]
	s_waitcnt lgkmcnt(0)
	v_mfma_f32_32x32x16_bf16 v[80:95], v[136:139], v[144:147], v[80:95]
	s_setprio 0
	s_sub_i32 s14, s50, 64
	s_cmp_le_u32 s14, s47
	s_cbranch_scc0 .LBB0_379
	v_mov_b32_e32 v0, s49
	ds_read_b32 v182, v0 offset:512
	s_mov_b64 s[14:15], 0
	s_branch .LBB0_380
